# base24 + HGRN2 step-3 o-product: k=2 operand pair read up front into dead quads
# speedup vs baseline: 1.0085x; 1.0031x over previous
; #define LAS __attribute__((address_space(3)))
; __device__ __forceinline__ bf16 bfr(float x) { return (bf16)cvt_pk_bf16(x, x); }
; __device__ __forceinline__ void st4bf(LAS bf16* p, float a, float b, float c, float d) { v2u w; w.x = cvt_pk_bf16(a, b); w.y = cvt_pk_bf16(c, d); *(LAS v2u*)p = w; }
; #define LBAR() asm volatile("s_waitcnt lgkmcnt(0)\n\ts_barrier" ::: "memory")
; __device__ __forceinline__ void phase_scan_chunk(const Args& a, LAS unsigned char* lds, const WCtx& w, int l) {
;     ...
;                 store_state_T(TST, S, wm, wn, r, hh);
;                 if (c + 1 < 36) GLA_LOAD(c + 1);
;                 LBAR();
;                 { f32x16 acc = zero16();
;                   if (wn >= wm) { const LAS bf16* Ap = (wm == 0 && wn == 0) ? TX + 32 * TS : TK + 32 * wm * TS; const LAS bf16* Bp = (wn == 0) ? TQ : TX;
;                       acc = mma64(acc, Ap, Bp, lane); }
;                   const int i = 32 * wn + r;
; #pragma unroll
;                   for (int q = 0; q < 4; ++q) { const int j0 = 32 * wm + 8 * q + 4 * hh;
;                       st4bf(TP + i * TS + j0, (j0 <= i) ? acc[4 * q] : 0.f, (j0 + 1 <= i) ? acc[4 * q + 1] : 0.f, (j0 + 2 <= i) ? acc[4 * q + 2] : 0.f, (j0 + 3 <= i) ? acc[4 * q + 3] : 0.f); } }
;                 LBAR();
;                 { bf16* sop = so + (size_t)chain_row(b, dir, c, 32 * wm + 4 * hh) * 256; const long sstep = dir ? -256 : 256;
;                   f32x16 o = zero16(); o = mma64s<false, true>(o, TP, wm, TVT, wn, lane); o = mma64(o, TQ + 32 * wm * TS, TST + 32 * wn * TS, lane);
;                   f32x16 ds = zero16(); ds = mma64s<true, true>(ds, TKD, wm, TVT, wn, lane);
; #pragma unroll
;                   for (int q = 0; q < 4; ++q) { const f32x4 dv = *(const LAS f32x4*)(DEC + 32 * wm + 8 * q + 4 * hh);
; #pragma unroll
;                       for (int t = 0; t < 4; ++t) { S[4 * q + t] = dv[t] * S[4 * q + t] + ds[4 * q + t]; sop[(long)(8 * q + t) * sstep] = bfr(o[4 * q + t]); } } }
;                 LBAR();
.LBB0_1432:
	s_nop 10
	v_cndmask_b32_e64 v2, v2, 0, s[46:47]
	v_cndmask_b32_e64 v3, 0, v3, s[48:49]
	v_cvt_pk_bf16_f32 v2, v2, v3
	v_cndmask_b32_e64 v4, v4, 0, s[50:51]
	v_cndmask_b32_e64 v5, v5, 0, s[52:53]
	v_cvt_pk_bf16_f32 v3, v4, v5
	ds_write_b64 v167, v[2:3] offset:55296
	v_cndmask_b32_e64 v2, v6, 0, s[54:55]
	v_cndmask_b32_e64 v3, 0, v7, s[56:57]
	v_cvt_pk_bf16_f32 v2, v2, v3
	v_cndmask_b32_e64 v4, v8, 0, s[58:59]
	v_cndmask_b32_e64 v5, v9, 0, s[60:61]
	v_cvt_pk_bf16_f32 v3, v4, v5
	ds_write_b64 v167, v[2:3] offset:55312
	v_cndmask_b32_e64 v2, v10, 0, s[62:63]
	v_cndmask_b32_e64 v3, 0, v11, s[64:65]
	v_cvt_pk_bf16_f32 v2, v2, v3
	s_cmp_lt_u32 s30, 4
	v_cndmask_b32_e64 v4, v12, 0, s[66:67]
	v_cndmask_b32_e64 v5, v13, 0, s[68:69]
	v_cvt_pk_bf16_f32 v3, v4, v5
	ds_write_b64 v167, v[2:3] offset:55328
	v_cndmask_b32_e64 v2, v14, 0, s[70:71]
	s_cselect_b64 vcc, -1, 0
	v_cndmask_b32_e64 v3, 0, v15, s[72:73]
	v_cvt_pk_bf16_f32 v2, v2, v3
	s_and_b64 s[2:3], vcc, exec
	v_cndmask_b32_e64 v4, v16, 0, s[74:75]
	v_cndmask_b32_e64 v5, v17, 0, s[76:77]
	v_cvt_pk_bf16_f32 v3, v4, v5
	ds_write_b64 v167, v[2:3] offset:55344
	v_cndmask_b32_e32 v2, v157, v123, vcc
	s_cselect_b32 s2, 0xff, s39
	v_add_u32_e32 v3, s29, v2
	v_sub_u32_e32 v2, s2, v2
	v_add_u32_e32 v2, s28, v2
	s_cselect_b32 s3, s26, s27
	v_cndmask_b32_e64 v2, v2, v3, s[0:1]
	v_add_u32_e32 v2, s3, v2
	v_ashrrev_i32_e32 v3, 31, v2
	v_lshlrev_b64 v[2:3], 9, v[2:3]
	s_waitcnt lgkmcnt(0)
	s_barrier
	v_lshl_add_u64 v[80:81], v[58:59], 0, v[2:3]
	v_add_u32_e32 v2, v128, v97
	ds_read_b128 v[2:5], v2 offset:55296
	v_add_u32_e32 v6, v125, v83
	ds_read_b128 v[18:21], v6 offset:36864
	v_add_u32_e32 v22, v128, v96
	ds_read_b128 v[22:25], v22 offset:55296
	s_waitcnt lgkmcnt(1)
	v_mfma_f32_32x32x16_bf16 v[2:17], v[2:5], v[18:21], 0
	v_add_u32_e32 v26, v125, v84
	ds_read_b128 v[34:37], v26 offset:36864
	v_add_u32_e32 v26, v125, v85
	ds_read_b128 v[220:223], v26 offset:36864
	v_add_u32_e32 v26, v125, v86
	ds_read_b128 v[242:245], v26 offset:36864
	v_add_u32_e32 v219, v128, v89
	s_waitcnt lgkmcnt(2)
	v_mfma_f32_32x32x16_bf16 v[2:17], v[22:25], v[34:37], v[2:17]
	v_add_u32_e32 v22, v128, v95
	ds_read_b128 v[22:25], v22 offset:55296
	s_add_i32 s29, s29, 64
	s_sub_i32 s28, s28, 64
	s_add_i32 s30, s30, 1
	s_cmpk_eq_i32 s29, 0x900
	s_waitcnt lgkmcnt(0)
	v_mfma_f32_32x32x16_bf16 v[2:17], v[22:25], v[220:223], v[2:17]
	v_add_u32_e32 v22, v128, v94
	ds_read_b128 v[22:25], v22 offset:55296
	s_waitcnt lgkmcnt(0)
	v_mfma_f32_32x32x16_bf16 v[2:17], v[22:25], v[242:245], v[2:17]
	ds_read_b128 v[22:25], v129
	ds_read_b128 v[26:29], v129 offset:32
	ds_read_b128 v[30:33], v130 offset:46080
	ds_read_b128 v[246:249], v130 offset:46112
	ds_read_b128 v[224:227], v129 offset:64
	ds_read_b128 v[238:241], v130 offset:46144
	s_waitcnt lgkmcnt(3)
	v_mfma_f32_32x32x16_bf16 v[2:17], v[22:25], v[30:33], v[2:17]
	s_waitcnt lgkmcnt(2)
	v_mfma_f32_32x32x16_bf16 v[2:17], v[26:29], v[246:249], v[2:17]
	s_waitcnt lgkmcnt(0)
	v_mfma_f32_32x32x16_bf16 v[2:17], v[224:227], v[238:241], v[2:17]
	ds_read_b128 v[22:25], v129 offset:96
	ds_read_b128 v[26:29], v130 offset:46176
	ds_read_b128 v[246:249], v219 offset:27648
	s_waitcnt lgkmcnt(1)
	v_mfma_f32_32x32x16_bf16 v[2:17], v[22:25], v[26:29], v[2:17]
	v_add_u32_e32 v22, v128, v88
	ds_read_b128 v[22:25], v22 offset:27648
	s_waitcnt lgkmcnt(0)
	v_mfma_f32_32x32x16_bf16 v[18:33], v[22:25], v[18:21], 0
	v_mfma_f32_32x32x16_bf16 v[18:33], v[246:249], v[34:37], v[18:33]
	v_add_u32_e32 v34, v128, v91
	ds_read_b128 v[34:37], v34 offset:27648
	s_waitcnt lgkmcnt(0)
	v_mfma_f32_32x32x16_bf16 v[18:33], v[34:37], v[220:223], v[18:33]
	v_add_u32_e32 v34, v128, v92
	ds_read_b128 v[34:37], v34 offset:27648
	s_waitcnt lgkmcnt(0)
	v_mfma_f32_32x32x16_bf16 v[18:33], v[34:37], v[242:245], v[18:33]
	ds_read_b128 v[34:37], v131 offset:65024
	v_cvt_pk_bf16_f32 v2, v2, v2
	global_store_short v[80:81], v2, off
	v_cvt_pk_bf16_f32 v219, v3, v3
	v_lshl_add_u64 v[2:3], v[52:53], 1, v[80:81]
	global_store_short v[2:3], v219, off
	v_cvt_pk_bf16_f32 v4, v4, v4
	v_lshl_add_u64 v[2:3], v[2:3], 0, v[54:55]
	global_store_short v[2:3], v4, off
	v_cvt_pk_bf16_f32 v4, v5, v5
	v_lshl_add_u64 v[80:81], v[2:3], 0, v[54:55]
	global_store_short v[80:81], v4, off
	ds_read_b128 v[2:5], v131 offset:65056
	v_cvt_pk_bf16_f32 v6, v6, v6
	v_lshl_add_u64 v[80:81], v[80:81], 0, v[56:57]
	global_store_short v[80:81], v6, off
	v_cvt_pk_bf16_f32 v219, v7, v7
	v_lshl_add_u64 v[6:7], v[80:81], 0, v[54:55]
	global_store_short v[6:7], v219, off
	v_cvt_pk_bf16_f32 v8, v8, v8
	v_lshl_add_u64 v[6:7], v[6:7], 0, v[54:55]
	global_store_short v[6:7], v8, off
	v_cvt_pk_bf16_f32 v8, v9, v9
	v_lshl_add_u64 v[80:81], v[6:7], 0, v[54:55]
	global_store_short v[80:81], v8, off
	ds_read_b128 v[6:9], v131 offset:65088
	v_cvt_pk_bf16_f32 v10, v10, v10
	v_lshl_add_u64 v[80:81], v[80:81], 0, v[56:57]
	global_store_short v[80:81], v10, off
	v_cvt_pk_bf16_f32 v219, v11, v11
	v_lshl_add_u64 v[10:11], v[80:81], 0, v[54:55]
	global_store_short v[10:11], v219, off
	v_cvt_pk_bf16_f32 v12, v12, v12
	v_lshl_add_u64 v[10:11], v[10:11], 0, v[54:55]
	global_store_short v[10:11], v12, off
	v_cvt_pk_bf16_f32 v12, v13, v13
	v_lshl_add_u64 v[80:81], v[10:11], 0, v[54:55]
	global_store_short v[80:81], v12, off
	ds_read_b128 v[10:13], v131 offset:65120
	v_cvt_pk_bf16_f32 v14, v14, v14
	v_lshl_add_u64 v[80:81], v[80:81], 0, v[56:57]
	global_store_short v[80:81], v14, off
	v_cvt_pk_bf16_f32 v219, v15, v15
	v_lshl_add_u64 v[14:15], v[80:81], 0, v[54:55]
	global_store_short v[14:15], v219, off
	v_lshl_add_u64 v[14:15], v[14:15], 0, v[54:55]
	s_waitcnt lgkmcnt(2)
	v_pk_fma_f32 v[68:69], v[68:69], v[2:3], v[22:23]
	v_lshl_add_u64 v[2:3], v[14:15], 0, v[54:55]
	v_cvt_pk_bf16_f32 v16, v16, v16
	global_store_short v[14:15], v16, off
	v_pk_fma_f32 v[70:71], v[70:71], v[4:5], v[24:25]
	v_cvt_pk_bf16_f32 v4, v17, v17
	global_store_short v[2:3], v4, off
	s_waitcnt lgkmcnt(0)
	s_barrier
	s_waitcnt lgkmcnt(0)
	v_pk_fma_f32 v[78:79], v[78:79], v[12:13], v[32:33]
	v_pk_fma_f32 v[76:77], v[76:77], v[10:11], v[30:31]
	v_pk_fma_f32 v[74:75], v[74:75], v[8:9], v[28:29]
	v_pk_fma_f32 v[72:73], v[72:73], v[6:7], v[26:27]
	v_pk_fma_f32 v[66:67], v[66:67], v[36:37], v[20:21]
	v_pk_fma_f32 v[64:65], v[64:65], v[34:35], v[18:19]
	s_cbranch_scc1 .LBB0_1430
